# phase 0: half of each XCD's workgroups run the row norm before the transposes and filter MLP (order swap)
# speedup vs baseline: 1.0223x; 1.0039x over previous
.Lp0_norm_done:
	s_or_b64 exec, exec, s[0:1]
	v_readlane_b32 s0, v255, 63
	s_nop 0
	s_cmp_eq_u32 s0, 1
	s_cbranch_scc0 .LBB0_22
	s_mov_b32 s0, 2
	v_writelane_b32 v255, s0, 63
	s_branch .Lp0_parts

.LBB0_298:
	s_andn2_b64 vcc, exec, s[0:1]
	s_cbranch_vccnz .LBB0_22
	v_readlane_b32 s0, v255, 25
	s_cmp_lg_u32 s0, 0
	s_cbranch_scc1 .LBB0_22
	s_bfe_u32 s0, s96, 0x10003
	v_writelane_b32 v255, s0, 63
	s_cmp_eq_u32 s0, 1
	s_cbranch_scc1 .LBB0_444
.Lp0_parts:
	v_mov_b32_e32 v0, v179
	s_nop 0
	v_cmp_gt_i32_e32 vcc, 64, v0
	s_and_saveexec_b64 s[28:29], vcc
	s_cbranch_execz .LBB0_302
	s_waitcnt lgkmcnt(0)
	v_cvt_f32_i32_e32 v1, v0
	s_mov_b32 s0, 0x7f800000
	v_lshl_add_u32 v0, v0, 2, 0
	v_mul_f32_e32 v1, 0x3d000000, v1
	v_mul_f32_e64 v3, |v1|, 0.5
	v_fract_f32_e32 v4, v3
	v_add_f32_e32 v4, v4, v4
	v_cmp_neq_f32_e32 vcc, s0, v3
	v_cmp_gt_f32_e64 s[0:1], |v1|, 1.0
	v_and_b32_e32 v2, 0x7fffffff, v1
	v_cndmask_b32_e32 v3, 0, v4, vcc
	v_cndmask_b32_e64 v3, |v1|, v3, s[0:1]
	v_add_f32_e32 v4, v3, v3
	v_rndne_f32_e32 v4, v4
	v_fmac_f32_e32 v3, -0.5, v4
	v_cvt_i32_f32_e32 v5, v4
	v_mul_f32_e32 v4, v3, v3
	v_fmamk_f32 v6, v4, 0x3e75aa41, v180
	v_fmaak_f32 v6, v4, v6, 0x40234736
	v_fmaak_f32 v6, v4, v6, 0xc0a55e0e
	s_waitcnt vmcnt(0)
	v_mul_f32_e32 v8, v3, v4
	v_mul_f32_e32 v6, v8, v6
	v_fmac_f32_e32 v6, 0x40490fdb, v3
	v_fmamk_f32 v3, v4, 0x3d4be544, v182
	v_fmaak_f32 v3, v4, v3, 0xbfaad1da
	v_fmaak_f32 v3, v4, v3, 0x4081e0d3
	v_fmaak_f32 v3, v4, v3, 0xc09de9e6
	v_fma_f32 v3, v4, v3, 1.0
	v_and_b32_e32 v4, 1, v5
	v_and_b32_e32 v7, 2, v5
	v_cmp_eq_u32_e32 vcc, 0, v4
	v_cmp_eq_u32_e64 s[0:1], 0, v7
	v_lshlrev_b32_e32 v5, 30, v5
	v_cndmask_b32_e64 v4, -v6, v3, vcc
	v_cndmask_b32_e64 v4, -v4, v4, s[0:1]
	s_movk_i32 s0, 0x1f8
	v_cmp_class_f32_e64 s[0:1], v1, s0
	v_and_b32_e32 v5, 0x80000000, v5
	v_xor_b32_e32 v1, v2, v1
	v_cndmask_b32_e32 v3, v3, v6, vcc
	v_xor_b32_e32 v1, v1, v5
	v_xor_b32_e32 v1, v1, v3
	v_cndmask_b32_e64 v4, v226, v4, s[0:1]
	v_cndmask_b32_e64 v1, v226, v1, s[0:1]
	ds_write2st64_b32 v0, v4, v1 offset0:65 offset1:66

.Lp0_after_filter:
	v_readlane_b32 s0, v255, 63
	s_nop 0
	s_cmp_eq_u32 s0, 2
	s_cbranch_scc1 .LBB0_22
